# hand-written merge phase: LDS fragment double-buffering, deferred last-ks MFMAs across barrier, saddr LDS-DMA
# speedup vs baseline: 1.0380x; 1.0380x over previous
.LBB0_1851:
	s_or_b64 exec, exec, s[0:1]
	v_readlane_b32 s0, v254, 12
	v_readlane_b32 s1, v254, 13
	s_andn2_b64 vcc, exec, s[0:1]
	s_waitcnt lgkmcnt(0)
	s_barrier
	s_cbranch_vccnz .LBB0_1914
	s_getreg_b32 s0, hwreg(HW_REG_HW_ID, 0, 6)
	s_lshl_b32 s0, s0, 2
	s_and_b32 s0, s0, 0xfc
	s_add_i32 s0, s0, 0x24800
	v_mov_b32_e32 v0, s0
	ds_read_b32 v0, v0
	v_mov_b32_e32 v220, 0x244d8
	ds_read2_b32 v[222:223], v220 offset1:1
	ds_read2_b32 v[224:225], v220 offset0:2 offset1:3
	v_mbcnt_lo_u32_b32 v221, -1, 0
	v_mbcnt_hi_u32_b32 v221, -1, v221
	s_waitcnt lgkmcnt(0)
	v_readfirstlane_b32 s38, v0
	v_readfirstlane_b32 s46, v222
	v_readfirstlane_b32 s47, v223
	v_readfirstlane_b32 s2, v224
	v_readfirstlane_b32 s3, v225
	v_readlane_b32 s40, v254, 55
	v_readlane_b32 s41, v254, 56
	v_readlane_b32 s24, v254, 11
	s_lshl_b32 s22, s38, 12
	s_lshl_b32 s25, s38, 11
	s_add_i32 s25, s25, 0x8000
	s_lshr_b32 s0, s38, 1
	s_and_b32 s1, s38, 1
	s_lshl_b32 s39, s0, 13
	s_lshl_b32 s30, s1, 13
	s_add_i32 s30, s30, 0x8000
	v_and_b32_e32 v220, 31, v221
	v_lshrrev_b32_e32 v222, 5, v221
	v_bfe_u32 v223, v221, 1, 3
	v_xor_b32_e32 v223, v223, v222
	v_lshlrev_b32_e32 v224, 7, v220
	v_lshl_or_b32 v225, v223, 4, v224
	v_add_u32_e32 v210, s39, v225
	v_add_u32_e32 v214, s30, v225
	v_xor_b32_e32 v226, 2, v223
	v_lshl_or_b32 v225, v226, 4, v224
	v_add_u32_e32 v211, s39, v225
	v_add_u32_e32 v215, s30, v225
	v_xor_b32_e32 v226, 4, v223
	v_lshl_or_b32 v225, v226, 4, v224
	v_add_u32_e32 v212, s39, v225
	v_add_u32_e32 v216, s30, v225
	v_xor_b32_e32 v226, 6, v223
	v_lshl_or_b32 v225, v226, 4, v224
	v_add_u32_e32 v213, s39, v225
	v_add_u32_e32 v217, s30, v225
	s_lshl_b32 s31, s0, 12
	v_lshlrev_b32_e32 v225, 6, v220
	v_add_u32_e32 v180, s31, v225
	s_lshl_b32 s31, s0, 17
	s_lshl_b32 s0, s1, 7
	s_add_i32 s31, s31, s0
	v_lshlrev_b32_e32 v225, 11, v220
	v_lshl_or_b32 v225, v222, 3, v225
	v_add_u32_e32 v178, s31, v225
	v_add_u32_e32 v179, 0x10000, v178
	v_and_b32_e32 v222, 7, v221
	v_bfe_u32 v223, v221, 4, 2
	v_xor_b32_e32 v222, v222, v223
	v_lshrrev_b32_e32 v223, 3, v221
	v_lshlrev_b32_e32 v224, 11, v223
	v_lshl_or_b32 v224, v222, 4, v224
	v_lshlrev_b32_e32 v225, 9, v223
	v_lshl_or_b32 v225, v222, 4, v225
	s_lshl_b32 s0, s38, 16
	s_add_i32 s1, s0, 0x0
	v_add_u32_e32 v202, s1, v224
	s_add_i32 s1, s0, 0x4000
	v_add_u32_e32 v203, s1, v224
	v_xor_b32_e32 v203, 64, v203
	s_add_i32 s1, s0, 0x8000
	v_add_u32_e32 v204, s1, v224
	s_add_i32 s1, s0, 0xc000
	v_add_u32_e32 v205, s1, v224
	v_xor_b32_e32 v205, 64, v205
	s_lshl_b32 s0, s38, 15
	s_add_i32 s1, s0, 0x0
	v_add_u32_e32 v206, s1, v224
	s_add_i32 s1, s0, 0x4000
	v_add_u32_e32 v207, s1, v224
	v_xor_b32_e32 v207, 64, v207
	s_lshl_b32 s0, s38, 13
	s_add_i32 s1, s0, 0x0
	v_add_u32_e32 v208, s1, v225
	s_add_i32 s1, s0, 0x1000
	v_add_u32_e32 v209, s1, v225
	v_xor_b32_e32 v209, 64, v209
	s_mov_b32 s21, 0
.Lmg_unit:
	s_lshr_b32 s0, s24, 3
	s_and_b32 s1, s24, 7
	s_lshl_b32 s30, s0, 19
	s_add_u32 s4, s46, s30
	s_addc_u32 s5, s47, 0
	s_add_u32 s6, s2, 0x8a00000
	s_addc_u32 s7, s3, 0
	s_add_u32 s6, s6, s30
	s_addc_u32 s7, s7, 0
	s_add_u32 s42, s2, 0xaa00000
	s_addc_u32 s43, s3, 0
	s_add_u32 s42, s42, s30
	s_addc_u32 s43, s43, 0
	s_lshl_b32 s31, s1, 8
	s_add_u32 s42, s42, s31
	s_addc_u32 s43, s43, 0
	s_add_u32 s44, s2, 0x10380000
	s_addc_u32 s45, s3, 0
	s_lshl_b32 s31, s0, 14
	s_add_u32 s44, s44, s31
	s_addc_u32 s45, s45, 0
	s_add_u32 s8, s40, 0x1600000
	s_addc_u32 s9, s41, 0
	s_lshl_b32 s31, s1, 18
	s_add_u32 s8, s8, s31
	s_addc_u32 s9, s9, 0
	s_add_u32 s10, s40, 0x1e00000
	s_addc_u32 s11, s41, 0
	s_lshl_b32 s31, s1, 16
	s_add_u32 s10, s10, s31
	s_addc_u32 s11, s11, 0
	s_waitcnt vmcnt(0)
	global_load_dwordx4 v[2:5], v180, s[44:45] offset:0
	global_load_dwordx4 v[6:9], v180, s[44:45] offset:16
	global_load_dwordx4 v[10:13], v180, s[44:45] offset:32
	global_load_dwordx4 v[14:17], v180, s[44:45] offset:48
	global_load_dwordx4 v[18:21], v180, s[44:45] offset:2048
	global_load_dwordx4 v[22:25], v180, s[44:45] offset:2064
	global_load_dwordx4 v[26:29], v180, s[44:45] offset:2080
	global_load_dwordx4 v[30:33], v180, s[44:45] offset:2096
	v_mov_b32_e32 v66, 0
	v_mov_b32_e32 v67, 0
	v_mov_b32_e32 v68, 0
	v_mov_b32_e32 v69, 0
	v_mov_b32_e32 v70, 0
	v_mov_b32_e32 v71, 0
	v_mov_b32_e32 v72, 0
	v_mov_b32_e32 v73, 0
	v_mov_b32_e32 v74, 0
	v_mov_b32_e32 v75, 0
	v_mov_b32_e32 v76, 0
	v_mov_b32_e32 v77, 0
	v_mov_b32_e32 v78, 0
	v_mov_b32_e32 v79, 0
	v_mov_b32_e32 v80, 0
	v_mov_b32_e32 v81, 0
	v_mov_b32_e32 v82, 0
	v_mov_b32_e32 v83, 0
	v_mov_b32_e32 v84, 0
	v_mov_b32_e32 v85, 0
	v_mov_b32_e32 v86, 0
	v_mov_b32_e32 v87, 0
	v_mov_b32_e32 v88, 0
	v_mov_b32_e32 v89, 0
	v_mov_b32_e32 v90, 0
	v_mov_b32_e32 v91, 0
	v_mov_b32_e32 v92, 0
	v_mov_b32_e32 v93, 0
	v_mov_b32_e32 v94, 0
	v_mov_b32_e32 v95, 0
	v_mov_b32_e32 v96, 0
	v_mov_b32_e32 v97, 0
	v_mov_b32_e32 v98, 0
	v_mov_b32_e32 v99, 0
	v_mov_b32_e32 v100, 0
	v_mov_b32_e32 v101, 0
	v_mov_b32_e32 v102, 0
	v_mov_b32_e32 v103, 0
	v_mov_b32_e32 v104, 0
	v_mov_b32_e32 v105, 0
	v_mov_b32_e32 v106, 0
	v_mov_b32_e32 v107, 0
	v_mov_b32_e32 v108, 0
	v_mov_b32_e32 v109, 0
	v_mov_b32_e32 v110, 0
	v_mov_b32_e32 v111, 0
	v_mov_b32_e32 v112, 0
	v_mov_b32_e32 v113, 0
	v_mov_b32_e32 v114, 0
	v_mov_b32_e32 v115, 0
	v_mov_b32_e32 v116, 0
	v_mov_b32_e32 v117, 0
	v_mov_b32_e32 v118, 0
	v_mov_b32_e32 v119, 0
	v_mov_b32_e32 v120, 0
	v_mov_b32_e32 v121, 0
	v_mov_b32_e32 v122, 0
	v_mov_b32_e32 v123, 0
	v_mov_b32_e32 v124, 0
	v_mov_b32_e32 v125, 0
	v_mov_b32_e32 v126, 0
	v_mov_b32_e32 v127, 0
	v_mov_b32_e32 v128, 0
	v_mov_b32_e32 v129, 0
	s_sub_i32 s23, 0, s21
	v_add_u32_e32 v210, s23, v210
	v_add_u32_e32 v214, s23, v214
	v_add_u32_e32 v211, s23, v211
	v_add_u32_e32 v215, s23, v215
	v_add_u32_e32 v212, s23, v212
	v_add_u32_e32 v216, s23, v216
	v_add_u32_e32 v213, s23, v213
	v_add_u32_e32 v217, s23, v217
	s_mov_b32 s21, 0
	v_mov_b32_e32 v220, 0x3a800000
	s_waitcnt vmcnt(0)
	v_add_f32_e32 v2, v2, v3
	v_add_f32_e32 v4, v4, v5
	v_add_f32_e32 v6, v6, v7
	v_add_f32_e32 v8, v8, v9
	v_add_f32_e32 v10, v10, v11
	v_add_f32_e32 v12, v12, v13
	v_add_f32_e32 v14, v14, v15
	v_add_f32_e32 v16, v16, v17
	v_add_f32_e32 v2, v2, v4
	v_add_f32_e32 v6, v6, v8
	v_add_f32_e32 v10, v10, v12
	v_add_f32_e32 v14, v14, v16
	v_add_f32_e32 v2, v2, v6
	v_add_f32_e32 v2, v2, v10
	v_add_f32_e32 v2, v2, v14
	v_fmamk_f32 v2, v2, 0x3a800000, v228
	v_rsq_f32_e32 v218, v2
	v_add_f32_e32 v18, v18, v19
	v_add_f32_e32 v20, v20, v21
	v_add_f32_e32 v22, v22, v23
	v_add_f32_e32 v24, v24, v25
	v_add_f32_e32 v26, v26, v27
	v_add_f32_e32 v28, v28, v29
	v_add_f32_e32 v30, v30, v31
	v_add_f32_e32 v32, v32, v33
	v_add_f32_e32 v18, v18, v20
	v_add_f32_e32 v22, v22, v24
	v_add_f32_e32 v26, v26, v28
	v_add_f32_e32 v30, v30, v32
	v_add_f32_e32 v18, v18, v22
	v_add_f32_e32 v18, v18, v26
	v_add_f32_e32 v18, v18, v30
	v_fmamk_f32 v18, v18, 0x3a800000, v228
	v_rsq_f32_e32 v219, v18
	s_add_u32 s12, s4, 0x0
	s_addc_u32 s13, s5, 0
	s_add_u32 s14, s8, 0x0
	s_addc_u32 s15, s9, 0
	s_add_i32 s28, s22, 0x0
	s_add_i32 s29, s25, 0x0
	s_add_i32 m0, s28, 0x0
	s_nop 0
	global_load_lds_dwordx4 v202, s[12:13]
	s_add_i32 m0, s28, 0x400
	s_nop 0
	global_load_lds_dwordx4 v203, s[12:13]
	s_add_i32 m0, s28, 0x800
	s_nop 0
	global_load_lds_dwordx4 v204, s[12:13]
	s_add_i32 m0, s28, 0xc00
	s_nop 0
	global_load_lds_dwordx4 v205, s[12:13]
	s_add_i32 m0, s29, 0x0
	s_nop 0
	global_load_lds_dwordx4 v206, s[14:15]
	s_add_i32 m0, s29, 0x400
	s_nop 0
	global_load_lds_dwordx4 v207, s[14:15]
	s_add_u32 s12, s12, 0x80
	s_addc_u32 s13, s13, 0
	s_add_u32 s14, s14, 0x80
	s_addc_u32 s15, s15, 0
	s_add_i32 s28, s22, 0xc000
	s_add_i32 s29, s25, 0xc000
	s_add_i32 m0, s28, 0x0
	s_nop 0
	global_load_lds_dwordx4 v202, s[12:13]
	s_add_i32 m0, s28, 0x400
	s_nop 0
	global_load_lds_dwordx4 v203, s[12:13]
	s_add_i32 m0, s28, 0x800
	s_nop 0
	global_load_lds_dwordx4 v204, s[12:13]
	s_add_i32 m0, s28, 0xc00
	s_nop 0
	global_load_lds_dwordx4 v205, s[12:13]
	s_add_i32 m0, s29, 0x0
	s_nop 0
	global_load_lds_dwordx4 v206, s[14:15]
	s_add_i32 m0, s29, 0x400
	s_nop 0
	global_load_lds_dwordx4 v207, s[14:15]
	s_add_u32 s12, s12, 0x80
	s_addc_u32 s13, s13, 0
	s_add_u32 s14, s14, 0x80
	s_addc_u32 s15, s15, 0
	s_mov_b32 s20, 0x18000
	s_mov_b32 s26, 0
.Lmg_iloop:
	s_lshl_b32 s30, s26, 21
	s_add_u32 s14, s8, s30
	s_addc_u32 s15, s9, 0
	s_add_u32 s14, s14, 0x100
	s_addc_u32 s15, s15, 0
	s_add_u32 s12, s4, 0x100
	s_addc_u32 s13, s5, 0
	s_lshl_b32 s30, s26, 9
	s_add_u32 s16, s6, s30
	s_addc_u32 s17, s7, 0
	s_lshl_b32 s30, s26, 19
	s_add_u32 s18, s10, s30
	s_addc_u32 s19, s11, 0
	s_add_i32 s30, s26, 1
	s_and_b32 s30, s30, 3
	s_lshl_b32 s30, s30, 21
	s_add_u32 s36, s8, s30
	s_addc_u32 s37, s9, 0
	s_add_u32 s34, s4, 0x0
	s_addc_u32 s35, s5, 0
	s_waitcnt vmcnt(6)
	s_barrier
	ds_read_b128 v[186:189], v214
	ds_read_b128 v[194:197], v210
	ds_read_b128 v[198:201], v210 offset:4096
	ds_read_b128 v[190:193], v214 offset:4096
	s_add_i32 s28, s20, s22
	s_add_i32 s29, s20, s25
	s_add_i32 m0, s28, 0x0
	s_nop 0
	global_load_lds_dwordx4 v202, s[12:13]
	s_add_i32 m0, s28, 0x400
	s_nop 0
	global_load_lds_dwordx4 v203, s[12:13]
	s_add_i32 m0, s28, 0x800
	s_nop 0
	global_load_lds_dwordx4 v204, s[12:13]
	s_add_i32 m0, s28, 0xc00
	s_nop 0
	global_load_lds_dwordx4 v205, s[12:13]
	ds_read_b128 v[162:165], v215
	ds_read_b128 v[170:173], v211
	ds_read_b128 v[174:177], v211 offset:4096
	ds_read_b128 v[166:169], v215 offset:4096
	s_waitcnt lgkmcnt(6)
	s_add_i32 m0, s29, 0x0
	v_mfma_f32_32x32x16_f16 v[2:17], v[186:189], v[194:197], 0
	global_load_lds_dwordx4 v206, s[14:15]
	s_waitcnt lgkmcnt(5)
	s_add_i32 m0, s29, 0x400
	v_mfma_f32_32x32x16_f16 v[18:33], v[186:189], v[198:201], 0
	global_load_lds_dwordx4 v207, s[14:15]
	s_waitcnt lgkmcnt(4)
	v_mfma_f32_32x32x16_f16 v[34:49], v[190:193], v[194:197], 0
	s_add_u32 s12, s12, 0x80
	s_addc_u32 s13, s13, 0
	v_mfma_f32_32x32x16_f16 v[50:65], v[190:193], v[198:201], 0
	s_add_u32 s14, s14, 0x80
	s_addc_u32 s15, s15, 0
	ds_read_b128 v[186:189], v216
	ds_read_b128 v[194:197], v212
	ds_read_b128 v[198:201], v212 offset:4096
	ds_read_b128 v[190:193], v216 offset:4096
	s_add_i32 s20, s20, 0xc000
	s_cmp_eq_u32 s20, 0x24000
	s_cselect_b32 s20, 0, s20
	s_waitcnt lgkmcnt(6)
	v_mfma_f32_32x32x16_f16 v[2:17], v[162:165], v[170:173], v[2:17]
	s_add_i32 s30, s21, 0xc000
	s_waitcnt lgkmcnt(5)
	v_mfma_f32_32x32x16_f16 v[18:33], v[162:165], v[174:177], v[18:33]
	s_cmp_eq_u32 s30, 0x24000
	s_waitcnt lgkmcnt(4)
	v_mfma_f32_32x32x16_f16 v[34:49], v[166:169], v[170:173], v[34:49]
	s_cselect_b32 s30, 0, s30
	v_mfma_f32_32x32x16_f16 v[50:65], v[166:169], v[174:177], v[50:65]
	s_sub_i32 s23, s30, s21
	s_mov_b32 s21, s30
	ds_read_b128 v[162:165], v217
	ds_read_b128 v[170:173], v213
	ds_read_b128 v[174:177], v213 offset:4096
	ds_read_b128 v[166:169], v217 offset:4096
	s_waitcnt lgkmcnt(6)
	v_mfma_f32_32x32x16_f16 v[2:17], v[186:189], v[194:197], v[2:17]
	v_add_u32_e32 v210, s23, v210
	v_add_u32_e32 v214, s23, v214
	s_waitcnt lgkmcnt(5)
	v_mfma_f32_32x32x16_f16 v[18:33], v[186:189], v[198:201], v[18:33]
	v_add_u32_e32 v211, s23, v211
	v_add_u32_e32 v215, s23, v215
	s_waitcnt lgkmcnt(4)
	v_mfma_f32_32x32x16_f16 v[34:49], v[190:193], v[194:197], v[34:49]
	v_add_u32_e32 v212, s23, v212
	v_add_u32_e32 v216, s23, v216
	v_mfma_f32_32x32x16_f16 v[50:65], v[190:193], v[198:201], v[50:65]
	v_add_u32_e32 v213, s23, v213
	v_add_u32_e32 v217, s23, v217
	s_waitcnt lgkmcnt(0)
	s_mov_b32 s27, 13
.Lmg_gloop:
	s_waitcnt vmcnt(6)
	s_barrier
	ds_read_b128 v[186:189], v214
	ds_read_b128 v[194:197], v210
	ds_read_b128 v[198:201], v210 offset:4096
	ds_read_b128 v[190:193], v214 offset:4096
	s_add_i32 s28, s20, s22
	s_add_i32 s29, s20, s25
	s_add_i32 m0, s28, 0x0
	v_mfma_f32_32x32x16_f16 v[2:17], v[162:165], v[170:173], v[2:17]
	global_load_lds_dwordx4 v202, s[12:13]
	s_add_i32 m0, s28, 0x400
	v_mfma_f32_32x32x16_f16 v[18:33], v[162:165], v[174:177], v[18:33]
	global_load_lds_dwordx4 v203, s[12:13]
	s_add_i32 m0, s28, 0x800
	v_mfma_f32_32x32x16_f16 v[34:49], v[166:169], v[170:173], v[34:49]
	global_load_lds_dwordx4 v204, s[12:13]
	s_add_i32 m0, s28, 0xc00
	v_mfma_f32_32x32x16_f16 v[50:65], v[166:169], v[174:177], v[50:65]
	global_load_lds_dwordx4 v205, s[12:13]
	ds_read_b128 v[162:165], v215
	ds_read_b128 v[170:173], v211
	ds_read_b128 v[174:177], v211 offset:4096
	ds_read_b128 v[166:169], v215 offset:4096
	s_waitcnt lgkmcnt(6)
	s_add_i32 m0, s29, 0x0
	v_mfma_f32_32x32x16_f16 v[2:17], v[186:189], v[194:197], v[2:17]
	global_load_lds_dwordx4 v206, s[14:15]
	s_waitcnt lgkmcnt(5)
	s_add_i32 m0, s29, 0x400
	v_mfma_f32_32x32x16_f16 v[18:33], v[186:189], v[198:201], v[18:33]
	global_load_lds_dwordx4 v207, s[14:15]
	s_waitcnt lgkmcnt(4)
	v_mfma_f32_32x32x16_f16 v[34:49], v[190:193], v[194:197], v[34:49]
	s_add_u32 s12, s12, 0x80
	s_addc_u32 s13, s13, 0
	v_mfma_f32_32x32x16_f16 v[50:65], v[190:193], v[198:201], v[50:65]
	s_add_u32 s14, s14, 0x80
	s_addc_u32 s15, s15, 0
	ds_read_b128 v[186:189], v216
	ds_read_b128 v[194:197], v212
	ds_read_b128 v[198:201], v212 offset:4096
	ds_read_b128 v[190:193], v216 offset:4096
	s_add_i32 s20, s20, 0xc000
	s_cmp_eq_u32 s20, 0x24000
	s_cselect_b32 s20, 0, s20
	s_waitcnt lgkmcnt(6)
	v_mfma_f32_32x32x16_f16 v[2:17], v[162:165], v[170:173], v[2:17]
	s_add_i32 s30, s21, 0xc000
	s_waitcnt lgkmcnt(5)
	v_mfma_f32_32x32x16_f16 v[18:33], v[162:165], v[174:177], v[18:33]
	s_cmp_eq_u32 s30, 0x24000
	s_waitcnt lgkmcnt(4)
	v_mfma_f32_32x32x16_f16 v[34:49], v[166:169], v[170:173], v[34:49]
	s_cselect_b32 s30, 0, s30
	v_mfma_f32_32x32x16_f16 v[50:65], v[166:169], v[174:177], v[50:65]
	s_sub_i32 s23, s30, s21
	s_mov_b32 s21, s30
	ds_read_b128 v[162:165], v217
	ds_read_b128 v[170:173], v213
	ds_read_b128 v[174:177], v213 offset:4096
	ds_read_b128 v[166:169], v217 offset:4096
	s_waitcnt lgkmcnt(6)
	v_mfma_f32_32x32x16_f16 v[2:17], v[186:189], v[194:197], v[2:17]
	v_add_u32_e32 v210, s23, v210
	v_add_u32_e32 v214, s23, v214
	s_waitcnt lgkmcnt(5)
	v_mfma_f32_32x32x16_f16 v[18:33], v[186:189], v[198:201], v[18:33]
	v_add_u32_e32 v211, s23, v211
	v_add_u32_e32 v215, s23, v215
	s_waitcnt lgkmcnt(4)
	v_mfma_f32_32x32x16_f16 v[34:49], v[190:193], v[194:197], v[34:49]
	v_add_u32_e32 v212, s23, v212
	v_add_u32_e32 v216, s23, v216
	v_mfma_f32_32x32x16_f16 v[50:65], v[190:193], v[198:201], v[50:65]
	v_add_u32_e32 v213, s23, v213
	v_add_u32_e32 v217, s23, v217
	s_waitcnt lgkmcnt(0)
	s_sub_i32 s27, s27, 1
	s_cmp_lg_u32 s27, 0
	s_cbranch_scc1 .Lmg_gloop
	s_waitcnt vmcnt(6)
	s_barrier
	ds_read_b128 v[186:189], v214
	ds_read_b128 v[194:197], v210
	ds_read_b128 v[198:201], v210 offset:4096
	ds_read_b128 v[190:193], v214 offset:4096
	s_add_i32 s28, s20, s22
	s_add_i32 s29, s20, s25
	s_add_i32 m0, s28, 0x0
	v_mfma_f32_32x32x16_f16 v[2:17], v[162:165], v[170:173], v[2:17]
	global_load_lds_dwordx4 v202, s[16:17]
	s_add_i32 m0, s28, 0x400
	v_mfma_f32_32x32x16_f16 v[18:33], v[162:165], v[174:177], v[18:33]
	global_load_lds_dwordx4 v203, s[16:17]
	s_add_i32 m0, s28, 0x800
	v_mfma_f32_32x32x16_f16 v[34:49], v[166:169], v[170:173], v[34:49]
	global_load_lds_dwordx4 v204, s[16:17]
	s_add_i32 m0, s28, 0xc00
	v_mfma_f32_32x32x16_f16 v[50:65], v[166:169], v[174:177], v[50:65]
	global_load_lds_dwordx4 v205, s[16:17]
	ds_read_b128 v[162:165], v215
	ds_read_b128 v[170:173], v211
	ds_read_b128 v[174:177], v211 offset:4096
	ds_read_b128 v[166:169], v215 offset:4096
	s_waitcnt lgkmcnt(6)
	s_add_i32 m0, s29, 0x0
	v_mfma_f32_32x32x16_f16 v[2:17], v[186:189], v[194:197], v[2:17]
	global_load_lds_dwordx4 v208, s[18:19]
	s_waitcnt lgkmcnt(5)
	s_add_i32 m0, s29, 0x400
	v_mfma_f32_32x32x16_f16 v[18:33], v[186:189], v[198:201], v[18:33]
	global_load_lds_dwordx4 v209, s[18:19]
	s_waitcnt lgkmcnt(4)
	v_mfma_f32_32x32x16_f16 v[34:49], v[190:193], v[194:197], v[34:49]
	s_add_u32 s16, s16, 0x80
	s_addc_u32 s17, s17, 0
	v_mfma_f32_32x32x16_f16 v[50:65], v[190:193], v[198:201], v[50:65]
	s_add_u32 s18, s18, 0x80
	s_addc_u32 s19, s19, 0
	ds_read_b128 v[186:189], v216
	ds_read_b128 v[194:197], v212
	ds_read_b128 v[198:201], v212 offset:4096
	ds_read_b128 v[190:193], v216 offset:4096
	s_add_i32 s20, s20, 0xc000
	s_cmp_eq_u32 s20, 0x24000
	s_cselect_b32 s20, 0, s20
	s_waitcnt lgkmcnt(6)
	v_mfma_f32_32x32x16_f16 v[2:17], v[162:165], v[170:173], v[2:17]
	s_add_i32 s30, s21, 0xc000
	s_waitcnt lgkmcnt(5)
	v_mfma_f32_32x32x16_f16 v[18:33], v[162:165], v[174:177], v[18:33]
	s_cmp_eq_u32 s30, 0x24000
	s_waitcnt lgkmcnt(4)
	v_mfma_f32_32x32x16_f16 v[34:49], v[166:169], v[170:173], v[34:49]
	s_cselect_b32 s30, 0, s30
	v_mfma_f32_32x32x16_f16 v[50:65], v[166:169], v[174:177], v[50:65]
	s_sub_i32 s23, s30, s21
	s_mov_b32 s21, s30
	ds_read_b128 v[162:165], v217
	ds_read_b128 v[170:173], v213
	ds_read_b128 v[174:177], v213 offset:4096
	ds_read_b128 v[166:169], v217 offset:4096
	s_waitcnt lgkmcnt(6)
	v_mfma_f32_32x32x16_f16 v[2:17], v[186:189], v[194:197], v[2:17]
	v_add_u32_e32 v210, s23, v210
	v_add_u32_e32 v214, s23, v214
	s_waitcnt lgkmcnt(5)
	v_mfma_f32_32x32x16_f16 v[18:33], v[186:189], v[198:201], v[18:33]
	v_add_u32_e32 v211, s23, v211
	v_add_u32_e32 v215, s23, v215
	s_waitcnt lgkmcnt(4)
	v_mfma_f32_32x32x16_f16 v[34:49], v[190:193], v[194:197], v[34:49]
	v_add_u32_e32 v212, s23, v212
	v_add_u32_e32 v216, s23, v216
	v_mfma_f32_32x32x16_f16 v[50:65], v[190:193], v[198:201], v[50:65]
	v_add_u32_e32 v213, s23, v213
	v_add_u32_e32 v217, s23, v217
	s_waitcnt lgkmcnt(0)
	s_waitcnt vmcnt(6)
	s_barrier
	ds_read_b128 v[186:189], v214
	ds_read_b128 v[194:197], v210
	ds_read_b128 v[198:201], v210 offset:4096
	ds_read_b128 v[190:193], v214 offset:4096
	s_add_i32 s28, s20, s22
	s_add_i32 s29, s20, s25
	s_add_i32 m0, s28, 0x0
	v_mfma_f32_32x32x16_f16 v[2:17], v[162:165], v[170:173], v[2:17]
	global_load_lds_dwordx4 v202, s[16:17]
	s_add_i32 m0, s28, 0x400
	v_mfma_f32_32x32x16_f16 v[18:33], v[162:165], v[174:177], v[18:33]
	global_load_lds_dwordx4 v203, s[16:17]
	s_add_i32 m0, s28, 0x800
	v_mfma_f32_32x32x16_f16 v[34:49], v[166:169], v[170:173], v[34:49]
	global_load_lds_dwordx4 v204, s[16:17]
	s_add_i32 m0, s28, 0xc00
	v_mfma_f32_32x32x16_f16 v[50:65], v[166:169], v[174:177], v[50:65]
	global_load_lds_dwordx4 v205, s[16:17]
	ds_read_b128 v[162:165], v215
	ds_read_b128 v[170:173], v211
	ds_read_b128 v[174:177], v211 offset:4096
	ds_read_b128 v[166:169], v215 offset:4096
	s_waitcnt lgkmcnt(6)
	s_add_i32 m0, s29, 0x0
	v_mfma_f32_32x32x16_f16 v[2:17], v[186:189], v[194:197], v[2:17]
	global_load_lds_dwordx4 v208, s[18:19]
	s_waitcnt lgkmcnt(5)
	s_add_i32 m0, s29, 0x400
	v_mfma_f32_32x32x16_f16 v[18:33], v[186:189], v[198:201], v[18:33]
	global_load_lds_dwordx4 v209, s[18:19]
	s_waitcnt lgkmcnt(4)
	v_mfma_f32_32x32x16_f16 v[34:49], v[190:193], v[194:197], v[34:49]
	s_add_u32 s16, s16, 0x80
	s_addc_u32 s17, s17, 0
	v_mfma_f32_32x32x16_f16 v[50:65], v[190:193], v[198:201], v[50:65]
	s_add_u32 s18, s18, 0x80
	s_addc_u32 s19, s19, 0
	ds_read_b128 v[186:189], v216
	ds_read_b128 v[194:197], v212
	ds_read_b128 v[198:201], v212 offset:4096
	ds_read_b128 v[190:193], v216 offset:4096
	s_add_i32 s20, s20, 0xc000
	s_cmp_eq_u32 s20, 0x24000
	s_cselect_b32 s20, 0, s20
	s_waitcnt lgkmcnt(6)
	v_mfma_f32_32x32x16_f16 v[2:17], v[162:165], v[170:173], v[2:17]
	s_add_i32 s30, s21, 0xc000
	s_waitcnt lgkmcnt(5)
	v_mfma_f32_32x32x16_f16 v[18:33], v[162:165], v[174:177], v[18:33]
	s_cmp_eq_u32 s30, 0x24000
	s_waitcnt lgkmcnt(4)
	v_mfma_f32_32x32x16_f16 v[34:49], v[166:169], v[170:173], v[34:49]
	s_cselect_b32 s30, 0, s30
	v_mfma_f32_32x32x16_f16 v[50:65], v[166:169], v[174:177], v[50:65]
	s_sub_i32 s23, s30, s21
	s_mov_b32 s21, s30
	ds_read_b128 v[162:165], v217
	ds_read_b128 v[170:173], v213
	ds_read_b128 v[174:177], v213 offset:4096
	ds_read_b128 v[166:169], v217 offset:4096
	s_waitcnt lgkmcnt(6)
	v_mfma_f32_32x32x16_f16 v[2:17], v[186:189], v[194:197], v[2:17]
	v_add_u32_e32 v210, s23, v210
	v_add_u32_e32 v214, s23, v214
	s_waitcnt lgkmcnt(5)
	v_mfma_f32_32x32x16_f16 v[18:33], v[186:189], v[198:201], v[18:33]
	v_add_u32_e32 v211, s23, v211
	v_add_u32_e32 v215, s23, v215
	s_waitcnt lgkmcnt(4)
	v_mfma_f32_32x32x16_f16 v[34:49], v[190:193], v[194:197], v[34:49]
	v_add_u32_e32 v212, s23, v212
	v_add_u32_e32 v216, s23, v216
	v_mfma_f32_32x32x16_f16 v[50:65], v[190:193], v[198:201], v[50:65]
	v_add_u32_e32 v213, s23, v213
	v_add_u32_e32 v217, s23, v217
	s_waitcnt lgkmcnt(0)
	v_mfma_f32_32x32x16_f16 v[2:17], v[162:165], v[170:173], v[2:17]
	v_mfma_f32_32x32x16_f16 v[18:33], v[162:165], v[174:177], v[18:33]
	v_mfma_f32_32x32x16_f16 v[34:49], v[166:169], v[170:173], v[34:49]
	v_mfma_f32_32x32x16_f16 v[50:65], v[166:169], v[174:177], v[50:65]
	s_nop 15
	v_mul_f32_e32 v2, v218, v2
	v_mul_f32_e32 v3, v218, v3
	v_mul_f32_e32 v4, v218, v4
	v_mul_f32_e32 v5, v218, v5
	v_mul_f32_e32 v6, v218, v6
	v_mul_f32_e32 v7, v218, v7
	v_mul_f32_e32 v8, v218, v8
	v_mul_f32_e32 v9, v218, v9
	v_mul_f32_e32 v2, 0xbfb8aa3b, v2
	v_mul_f32_e32 v3, 0xbfb8aa3b, v3
	v_mul_f32_e32 v4, 0xbfb8aa3b, v4
	v_mul_f32_e32 v5, 0xbfb8aa3b, v5
	v_mul_f32_e32 v6, 0xbfb8aa3b, v6
	v_mul_f32_e32 v7, 0xbfb8aa3b, v7
	v_mul_f32_e32 v8, 0xbfb8aa3b, v8
	v_mul_f32_e32 v9, 0xbfb8aa3b, v9
	v_exp_f32_e32 v2, v2
	v_exp_f32_e32 v3, v3
	v_exp_f32_e32 v4, v4
	v_exp_f32_e32 v5, v5
	v_exp_f32_e32 v6, v6
	v_exp_f32_e32 v7, v7
	v_exp_f32_e32 v8, v8
	v_exp_f32_e32 v9, v9
	v_add_f32_e32 v2, 1.0, v2
	v_add_f32_e32 v3, 1.0, v3
	v_add_f32_e32 v4, 1.0, v4
	v_add_f32_e32 v5, 1.0, v5
	v_add_f32_e32 v6, 1.0, v6
	v_add_f32_e32 v7, 1.0, v7
	v_add_f32_e32 v8, 1.0, v8
	v_add_f32_e32 v9, 1.0, v9
	v_rcp_f32_e32 v2, v2
	v_rcp_f32_e32 v3, v3
	v_rcp_f32_e32 v4, v4
	v_rcp_f32_e32 v5, v5
	v_rcp_f32_e32 v6, v6
	v_rcp_f32_e32 v7, v7
	v_rcp_f32_e32 v8, v8
	v_rcp_f32_e32 v9, v9
	v_cvt_pk_bf16_f32 v130, v2, v3
	v_cvt_pk_bf16_f32 v131, v4, v5
	v_cvt_pk_bf16_f32 v132, v6, v7
	v_cvt_pk_bf16_f32 v133, v8, v9
	v_mul_f32_e32 v10, v218, v10
	v_mul_f32_e32 v11, v218, v11
	v_mul_f32_e32 v12, v218, v12
	v_mul_f32_e32 v13, v218, v13
	v_mul_f32_e32 v14, v218, v14
	v_mul_f32_e32 v15, v218, v15
	v_mul_f32_e32 v16, v218, v16
	v_mul_f32_e32 v17, v218, v17
	v_mul_f32_e32 v10, 0xbfb8aa3b, v10
	v_mul_f32_e32 v11, 0xbfb8aa3b, v11
	v_mul_f32_e32 v12, 0xbfb8aa3b, v12
	v_mul_f32_e32 v13, 0xbfb8aa3b, v13
	v_mul_f32_e32 v14, 0xbfb8aa3b, v14
	v_mul_f32_e32 v15, 0xbfb8aa3b, v15
	v_mul_f32_e32 v16, 0xbfb8aa3b, v16
	v_mul_f32_e32 v17, 0xbfb8aa3b, v17
	v_exp_f32_e32 v10, v10
	v_exp_f32_e32 v11, v11
	v_exp_f32_e32 v12, v12
	v_exp_f32_e32 v13, v13
	v_exp_f32_e32 v14, v14
	v_exp_f32_e32 v15, v15
	v_exp_f32_e32 v16, v16
	v_exp_f32_e32 v17, v17
	v_add_f32_e32 v10, 1.0, v10
	v_add_f32_e32 v11, 1.0, v11
	v_add_f32_e32 v12, 1.0, v12
	v_add_f32_e32 v13, 1.0, v13
	v_add_f32_e32 v14, 1.0, v14
	v_add_f32_e32 v15, 1.0, v15
	v_add_f32_e32 v16, 1.0, v16
	v_add_f32_e32 v17, 1.0, v17
	v_rcp_f32_e32 v10, v10
	v_rcp_f32_e32 v11, v11
	v_rcp_f32_e32 v12, v12
	v_rcp_f32_e32 v13, v13
	v_rcp_f32_e32 v14, v14
	v_rcp_f32_e32 v15, v15
	v_rcp_f32_e32 v16, v16
	v_rcp_f32_e32 v17, v17
	v_cvt_pk_bf16_f32 v134, v10, v11
	v_cvt_pk_bf16_f32 v135, v12, v13
	v_cvt_pk_bf16_f32 v136, v14, v15
	v_cvt_pk_bf16_f32 v137, v16, v17
	v_mul_f32_e32 v18, v219, v18
	v_mul_f32_e32 v19, v219, v19
	v_mul_f32_e32 v20, v219, v20
	v_mul_f32_e32 v21, v219, v21
	v_mul_f32_e32 v22, v219, v22
	v_mul_f32_e32 v23, v219, v23
	v_mul_f32_e32 v24, v219, v24
	v_mul_f32_e32 v25, v219, v25
	v_mul_f32_e32 v18, 0xbfb8aa3b, v18
	v_mul_f32_e32 v19, 0xbfb8aa3b, v19
	v_mul_f32_e32 v20, 0xbfb8aa3b, v20
	v_mul_f32_e32 v21, 0xbfb8aa3b, v21
	v_mul_f32_e32 v22, 0xbfb8aa3b, v22
	v_mul_f32_e32 v23, 0xbfb8aa3b, v23
	v_mul_f32_e32 v24, 0xbfb8aa3b, v24
	v_mul_f32_e32 v25, 0xbfb8aa3b, v25
	v_exp_f32_e32 v18, v18
	v_exp_f32_e32 v19, v19
	v_exp_f32_e32 v20, v20
	v_exp_f32_e32 v21, v21
	v_exp_f32_e32 v22, v22
	v_exp_f32_e32 v23, v23
	v_exp_f32_e32 v24, v24
	v_exp_f32_e32 v25, v25
	v_add_f32_e32 v18, 1.0, v18
	v_add_f32_e32 v19, 1.0, v19
	v_add_f32_e32 v20, 1.0, v20
	v_add_f32_e32 v21, 1.0, v21
	v_add_f32_e32 v22, 1.0, v22
	v_add_f32_e32 v23, 1.0, v23
	v_add_f32_e32 v24, 1.0, v24
	v_add_f32_e32 v25, 1.0, v25
	v_rcp_f32_e32 v18, v18
	v_rcp_f32_e32 v19, v19
	v_rcp_f32_e32 v20, v20
	v_rcp_f32_e32 v21, v21
	v_rcp_f32_e32 v22, v22
	v_rcp_f32_e32 v23, v23
	v_rcp_f32_e32 v24, v24
	v_rcp_f32_e32 v25, v25
	v_cvt_pk_bf16_f32 v138, v18, v19
	v_cvt_pk_bf16_f32 v139, v20, v21
	v_cvt_pk_bf16_f32 v140, v22, v23
	v_cvt_pk_bf16_f32 v141, v24, v25
	v_mul_f32_e32 v26, v219, v26
	v_mul_f32_e32 v27, v219, v27
	v_mul_f32_e32 v28, v219, v28
	v_mul_f32_e32 v29, v219, v29
	v_mul_f32_e32 v30, v219, v30
	v_mul_f32_e32 v31, v219, v31
	v_mul_f32_e32 v32, v219, v32
	v_mul_f32_e32 v33, v219, v33
	v_mul_f32_e32 v26, 0xbfb8aa3b, v26
	v_mul_f32_e32 v27, 0xbfb8aa3b, v27
	v_mul_f32_e32 v28, 0xbfb8aa3b, v28
	v_mul_f32_e32 v29, 0xbfb8aa3b, v29
	v_mul_f32_e32 v30, 0xbfb8aa3b, v30
	v_mul_f32_e32 v31, 0xbfb8aa3b, v31
	v_mul_f32_e32 v32, 0xbfb8aa3b, v32
	v_mul_f32_e32 v33, 0xbfb8aa3b, v33
	v_exp_f32_e32 v26, v26
	v_exp_f32_e32 v27, v27
	v_exp_f32_e32 v28, v28
	v_exp_f32_e32 v29, v29
	v_exp_f32_e32 v30, v30
	v_exp_f32_e32 v31, v31
	v_exp_f32_e32 v32, v32
	v_exp_f32_e32 v33, v33
	v_add_f32_e32 v26, 1.0, v26
	v_add_f32_e32 v27, 1.0, v27
	v_add_f32_e32 v28, 1.0, v28
	v_add_f32_e32 v29, 1.0, v29
	v_add_f32_e32 v30, 1.0, v30
	v_add_f32_e32 v31, 1.0, v31
	v_add_f32_e32 v32, 1.0, v32
	v_add_f32_e32 v33, 1.0, v33
	v_rcp_f32_e32 v26, v26
	v_rcp_f32_e32 v27, v27
	v_rcp_f32_e32 v28, v28
	v_rcp_f32_e32 v29, v29
	v_rcp_f32_e32 v30, v30
	v_rcp_f32_e32 v31, v31
	v_rcp_f32_e32 v32, v32
	v_rcp_f32_e32 v33, v33
	v_cvt_pk_bf16_f32 v142, v26, v27
	v_cvt_pk_bf16_f32 v143, v28, v29
	v_cvt_pk_bf16_f32 v144, v30, v31
	v_cvt_pk_bf16_f32 v145, v32, v33
	v_mul_f32_e32 v34, v218, v34
	v_mul_f32_e32 v35, v218, v35
	v_mul_f32_e32 v36, v218, v36
	v_mul_f32_e32 v37, v218, v37
	v_mul_f32_e32 v38, v218, v38
	v_mul_f32_e32 v39, v218, v39
	v_mul_f32_e32 v40, v218, v40
	v_mul_f32_e32 v41, v218, v41
	v_mul_f32_e32 v34, 0xbfb8aa3b, v34
	v_mul_f32_e32 v35, 0xbfb8aa3b, v35
	v_mul_f32_e32 v36, 0xbfb8aa3b, v36
	v_mul_f32_e32 v37, 0xbfb8aa3b, v37
	v_mul_f32_e32 v38, 0xbfb8aa3b, v38
	v_mul_f32_e32 v39, 0xbfb8aa3b, v39
	v_mul_f32_e32 v40, 0xbfb8aa3b, v40
	v_mul_f32_e32 v41, 0xbfb8aa3b, v41
	v_exp_f32_e32 v34, v34
	v_exp_f32_e32 v35, v35
	v_exp_f32_e32 v36, v36
	v_exp_f32_e32 v37, v37
	v_exp_f32_e32 v38, v38
	v_exp_f32_e32 v39, v39
	v_exp_f32_e32 v40, v40
	v_exp_f32_e32 v41, v41
	v_add_f32_e32 v34, 1.0, v34
	v_add_f32_e32 v35, 1.0, v35
	v_add_f32_e32 v36, 1.0, v36
	v_add_f32_e32 v37, 1.0, v37
	v_add_f32_e32 v38, 1.0, v38
	v_add_f32_e32 v39, 1.0, v39
	v_add_f32_e32 v40, 1.0, v40
	v_add_f32_e32 v41, 1.0, v41
	v_rcp_f32_e32 v34, v34
	v_rcp_f32_e32 v35, v35
	v_rcp_f32_e32 v36, v36
	v_rcp_f32_e32 v37, v37
	v_rcp_f32_e32 v38, v38
	v_rcp_f32_e32 v39, v39
	v_rcp_f32_e32 v40, v40
	v_rcp_f32_e32 v41, v41
	v_cvt_pk_bf16_f32 v146, v34, v35
	v_cvt_pk_bf16_f32 v147, v36, v37
	v_cvt_pk_bf16_f32 v148, v38, v39
	v_cvt_pk_bf16_f32 v149, v40, v41
	v_mul_f32_e32 v42, v218, v42
	v_mul_f32_e32 v43, v218, v43
	v_mul_f32_e32 v44, v218, v44
	v_mul_f32_e32 v45, v218, v45
	v_mul_f32_e32 v46, v218, v46
	v_mul_f32_e32 v47, v218, v47
	v_mul_f32_e32 v48, v218, v48
	v_mul_f32_e32 v49, v218, v49
	v_mul_f32_e32 v42, 0xbfb8aa3b, v42
	v_mul_f32_e32 v43, 0xbfb8aa3b, v43
	v_mul_f32_e32 v44, 0xbfb8aa3b, v44
	v_mul_f32_e32 v45, 0xbfb8aa3b, v45
	v_mul_f32_e32 v46, 0xbfb8aa3b, v46
	v_mul_f32_e32 v47, 0xbfb8aa3b, v47
	v_mul_f32_e32 v48, 0xbfb8aa3b, v48
	v_mul_f32_e32 v49, 0xbfb8aa3b, v49
	v_exp_f32_e32 v42, v42
	v_exp_f32_e32 v43, v43
	v_exp_f32_e32 v44, v44
	v_exp_f32_e32 v45, v45
	v_exp_f32_e32 v46, v46
	v_exp_f32_e32 v47, v47
	v_exp_f32_e32 v48, v48
	v_exp_f32_e32 v49, v49
	v_add_f32_e32 v42, 1.0, v42
	v_add_f32_e32 v43, 1.0, v43
	v_add_f32_e32 v44, 1.0, v44
	v_add_f32_e32 v45, 1.0, v45
	v_add_f32_e32 v46, 1.0, v46
	v_add_f32_e32 v47, 1.0, v47
	v_add_f32_e32 v48, 1.0, v48
	v_add_f32_e32 v49, 1.0, v49
	v_rcp_f32_e32 v42, v42
	v_rcp_f32_e32 v43, v43
	v_rcp_f32_e32 v44, v44
	v_rcp_f32_e32 v45, v45
	v_rcp_f32_e32 v46, v46
	v_rcp_f32_e32 v47, v47
	v_rcp_f32_e32 v48, v48
	v_rcp_f32_e32 v49, v49
	v_cvt_pk_bf16_f32 v150, v42, v43
	v_cvt_pk_bf16_f32 v151, v44, v45
	v_cvt_pk_bf16_f32 v152, v46, v47
	v_cvt_pk_bf16_f32 v153, v48, v49
	v_mul_f32_e32 v50, v219, v50
	v_mul_f32_e32 v51, v219, v51
	v_mul_f32_e32 v52, v219, v52
	v_mul_f32_e32 v53, v219, v53
	v_mul_f32_e32 v54, v219, v54
	v_mul_f32_e32 v55, v219, v55
	v_mul_f32_e32 v56, v219, v56
	v_mul_f32_e32 v57, v219, v57
	v_mul_f32_e32 v50, 0xbfb8aa3b, v50
	v_mul_f32_e32 v51, 0xbfb8aa3b, v51
	v_mul_f32_e32 v52, 0xbfb8aa3b, v52
	v_mul_f32_e32 v53, 0xbfb8aa3b, v53
	v_mul_f32_e32 v54, 0xbfb8aa3b, v54
	v_mul_f32_e32 v55, 0xbfb8aa3b, v55
	v_mul_f32_e32 v56, 0xbfb8aa3b, v56
	v_mul_f32_e32 v57, 0xbfb8aa3b, v57
	v_exp_f32_e32 v50, v50
	v_exp_f32_e32 v51, v51
	v_exp_f32_e32 v52, v52
	v_exp_f32_e32 v53, v53
	v_exp_f32_e32 v54, v54
	v_exp_f32_e32 v55, v55
	v_exp_f32_e32 v56, v56
	v_exp_f32_e32 v57, v57
	v_add_f32_e32 v50, 1.0, v50
	v_add_f32_e32 v51, 1.0, v51
	v_add_f32_e32 v52, 1.0, v52
	v_add_f32_e32 v53, 1.0, v53
	v_add_f32_e32 v54, 1.0, v54
	v_add_f32_e32 v55, 1.0, v55
	v_add_f32_e32 v56, 1.0, v56
	v_add_f32_e32 v57, 1.0, v57
	v_rcp_f32_e32 v50, v50
	v_rcp_f32_e32 v51, v51
	v_rcp_f32_e32 v52, v52
	v_rcp_f32_e32 v53, v53
	v_rcp_f32_e32 v54, v54
	v_rcp_f32_e32 v55, v55
	v_rcp_f32_e32 v56, v56
	v_rcp_f32_e32 v57, v57
	v_cvt_pk_bf16_f32 v154, v50, v51
	v_cvt_pk_bf16_f32 v155, v52, v53
	v_cvt_pk_bf16_f32 v156, v54, v55
	v_cvt_pk_bf16_f32 v157, v56, v57
	v_mul_f32_e32 v58, v219, v58
	v_mul_f32_e32 v59, v219, v59
	v_mul_f32_e32 v60, v219, v60
	v_mul_f32_e32 v61, v219, v61
	v_mul_f32_e32 v62, v219, v62
	v_mul_f32_e32 v63, v219, v63
	v_mul_f32_e32 v64, v219, v64
	v_mul_f32_e32 v65, v219, v65
	v_mul_f32_e32 v58, 0xbfb8aa3b, v58
	v_mul_f32_e32 v59, 0xbfb8aa3b, v59
	v_mul_f32_e32 v60, 0xbfb8aa3b, v60
	v_mul_f32_e32 v61, 0xbfb8aa3b, v61
	v_mul_f32_e32 v62, 0xbfb8aa3b, v62
	v_mul_f32_e32 v63, 0xbfb8aa3b, v63
	v_mul_f32_e32 v64, 0xbfb8aa3b, v64
	v_mul_f32_e32 v65, 0xbfb8aa3b, v65
	v_exp_f32_e32 v58, v58
	v_exp_f32_e32 v59, v59
	v_exp_f32_e32 v60, v60
	v_exp_f32_e32 v61, v61
	v_exp_f32_e32 v62, v62
	v_exp_f32_e32 v63, v63
	v_exp_f32_e32 v64, v64
	v_exp_f32_e32 v65, v65
	v_add_f32_e32 v58, 1.0, v58
	v_add_f32_e32 v59, 1.0, v59
	v_add_f32_e32 v60, 1.0, v60
	v_add_f32_e32 v61, 1.0, v61
	v_add_f32_e32 v62, 1.0, v62
	v_add_f32_e32 v63, 1.0, v63
	v_add_f32_e32 v64, 1.0, v64
	v_add_f32_e32 v65, 1.0, v65
	v_rcp_f32_e32 v58, v58
	v_rcp_f32_e32 v59, v59
	v_rcp_f32_e32 v60, v60
	v_rcp_f32_e32 v61, v61
	v_rcp_f32_e32 v62, v62
	v_rcp_f32_e32 v63, v63
	v_rcp_f32_e32 v64, v64
	v_rcp_f32_e32 v65, v65
	v_cvt_pk_bf16_f32 v158, v58, v59
	v_cvt_pk_bf16_f32 v159, v60, v61
	v_cvt_pk_bf16_f32 v160, v62, v63
	v_cvt_pk_bf16_f32 v161, v64, v65
	s_waitcnt vmcnt(6)
	s_barrier
	ds_read_b128 v[186:189], v214
	ds_read_b128 v[194:197], v210
	ds_read_b128 v[198:201], v210 offset:4096
	ds_read_b128 v[190:193], v214 offset:4096
	s_add_i32 s28, s20, s22
	s_add_i32 s29, s20, s25
	s_add_i32 m0, s28, 0x0
	s_nop 0
	global_load_lds_dwordx4 v202, s[16:17]
	s_add_i32 m0, s28, 0x400
	s_nop 0
	global_load_lds_dwordx4 v203, s[16:17]
	s_add_i32 m0, s28, 0x800
	s_nop 0
	global_load_lds_dwordx4 v204, s[16:17]
	s_add_i32 m0, s28, 0xc00
	s_nop 0
	global_load_lds_dwordx4 v205, s[16:17]
	ds_read_b128 v[162:165], v215
	ds_read_b128 v[170:173], v211
	ds_read_b128 v[174:177], v211 offset:4096
	ds_read_b128 v[166:169], v215 offset:4096
	s_waitcnt lgkmcnt(6)
	s_add_i32 m0, s29, 0x0
	v_mfma_f32_32x32x16_bf16 v[2:17], v[186:189], v[194:197], 0
	global_load_lds_dwordx4 v208, s[18:19]
	s_waitcnt lgkmcnt(5)
	s_add_i32 m0, s29, 0x400
	v_mfma_f32_32x32x16_bf16 v[18:33], v[186:189], v[198:201], 0
	global_load_lds_dwordx4 v209, s[18:19]
	s_waitcnt lgkmcnt(4)
	v_mfma_f32_32x32x16_bf16 v[34:49], v[190:193], v[194:197], 0
	s_add_u32 s16, s16, 0x80
	s_addc_u32 s17, s17, 0
	v_mfma_f32_32x32x16_bf16 v[50:65], v[190:193], v[198:201], 0
	s_add_u32 s18, s18, 0x80
	s_addc_u32 s19, s19, 0
	ds_read_b128 v[186:189], v216
	ds_read_b128 v[194:197], v212
	ds_read_b128 v[198:201], v212 offset:4096
	ds_read_b128 v[190:193], v216 offset:4096
	s_add_i32 s20, s20, 0xc000
	s_cmp_eq_u32 s20, 0x24000
	s_cselect_b32 s20, 0, s20
	s_waitcnt lgkmcnt(6)
	v_mfma_f32_32x32x16_bf16 v[2:17], v[162:165], v[170:173], v[2:17]
	s_add_i32 s30, s21, 0xc000
	s_waitcnt lgkmcnt(5)
	v_mfma_f32_32x32x16_bf16 v[18:33], v[162:165], v[174:177], v[18:33]
	s_cmp_eq_u32 s30, 0x24000
	s_waitcnt lgkmcnt(4)
	v_mfma_f32_32x32x16_bf16 v[34:49], v[166:169], v[170:173], v[34:49]
	s_cselect_b32 s30, 0, s30
	v_mfma_f32_32x32x16_bf16 v[50:65], v[166:169], v[174:177], v[50:65]
	s_sub_i32 s23, s30, s21
	s_mov_b32 s21, s30
	ds_read_b128 v[162:165], v217
	ds_read_b128 v[170:173], v213
	ds_read_b128 v[174:177], v213 offset:4096
	ds_read_b128 v[166:169], v217 offset:4096
	s_waitcnt lgkmcnt(6)
	v_mfma_f32_32x32x16_bf16 v[2:17], v[186:189], v[194:197], v[2:17]
	v_add_u32_e32 v210, s23, v210
	v_add_u32_e32 v214, s23, v214
	s_waitcnt lgkmcnt(5)
	v_mfma_f32_32x32x16_bf16 v[18:33], v[186:189], v[198:201], v[18:33]
	v_add_u32_e32 v211, s23, v211
	v_add_u32_e32 v215, s23, v215
	s_waitcnt lgkmcnt(4)
	v_mfma_f32_32x32x16_bf16 v[34:49], v[190:193], v[194:197], v[34:49]
	v_add_u32_e32 v212, s23, v212
	v_add_u32_e32 v216, s23, v216
	v_mfma_f32_32x32x16_bf16 v[50:65], v[190:193], v[198:201], v[50:65]
	v_add_u32_e32 v213, s23, v213
	v_add_u32_e32 v217, s23, v217
	s_waitcnt lgkmcnt(0)
	s_waitcnt vmcnt(6)
	s_barrier
	ds_read_b128 v[186:189], v214
	ds_read_b128 v[194:197], v210
	ds_read_b128 v[198:201], v210 offset:4096
	ds_read_b128 v[190:193], v214 offset:4096
	s_add_i32 s28, s20, s22
	s_add_i32 s29, s20, s25
	s_add_i32 m0, s28, 0x0
	v_mfma_f32_32x32x16_bf16 v[2:17], v[162:165], v[170:173], v[2:17]
	global_load_lds_dwordx4 v202, s[16:17]
	s_add_i32 m0, s28, 0x400
	v_mfma_f32_32x32x16_bf16 v[18:33], v[162:165], v[174:177], v[18:33]
	global_load_lds_dwordx4 v203, s[16:17]
	s_add_i32 m0, s28, 0x800
	v_mfma_f32_32x32x16_bf16 v[34:49], v[166:169], v[170:173], v[34:49]
	global_load_lds_dwordx4 v204, s[16:17]
	s_add_i32 m0, s28, 0xc00
	v_mfma_f32_32x32x16_bf16 v[50:65], v[166:169], v[174:177], v[50:65]
	global_load_lds_dwordx4 v205, s[16:17]
	ds_read_b128 v[162:165], v215
	ds_read_b128 v[170:173], v211
	ds_read_b128 v[174:177], v211 offset:4096
	ds_read_b128 v[166:169], v215 offset:4096
	s_waitcnt lgkmcnt(6)
	s_add_i32 m0, s29, 0x0
	v_mfma_f32_32x32x16_bf16 v[2:17], v[186:189], v[194:197], v[2:17]
	global_load_lds_dwordx4 v208, s[18:19]
	s_waitcnt lgkmcnt(5)
	s_add_i32 m0, s29, 0x400
	v_mfma_f32_32x32x16_bf16 v[18:33], v[186:189], v[198:201], v[18:33]
	global_load_lds_dwordx4 v209, s[18:19]
	s_waitcnt lgkmcnt(4)
	v_mfma_f32_32x32x16_bf16 v[34:49], v[190:193], v[194:197], v[34:49]
	s_add_u32 s16, s16, 0x80
	s_addc_u32 s17, s17, 0
	v_mfma_f32_32x32x16_bf16 v[50:65], v[190:193], v[198:201], v[50:65]
	s_add_u32 s18, s18, 0x80
	s_addc_u32 s19, s19, 0
	ds_read_b128 v[186:189], v216
	ds_read_b128 v[194:197], v212
	ds_read_b128 v[198:201], v212 offset:4096
	ds_read_b128 v[190:193], v216 offset:4096
	s_add_i32 s20, s20, 0xc000
	s_cmp_eq_u32 s20, 0x24000
	s_cselect_b32 s20, 0, s20
	s_waitcnt lgkmcnt(6)
	v_mfma_f32_32x32x16_bf16 v[2:17], v[162:165], v[170:173], v[2:17]
	s_add_i32 s30, s21, 0xc000
	s_waitcnt lgkmcnt(5)
	v_mfma_f32_32x32x16_bf16 v[18:33], v[162:165], v[174:177], v[18:33]
	s_cmp_eq_u32 s30, 0x24000
	s_waitcnt lgkmcnt(4)
	v_mfma_f32_32x32x16_bf16 v[34:49], v[166:169], v[170:173], v[34:49]
	s_cselect_b32 s30, 0, s30
	v_mfma_f32_32x32x16_bf16 v[50:65], v[166:169], v[174:177], v[50:65]
	s_sub_i32 s23, s30, s21
	s_mov_b32 s21, s30
	ds_read_b128 v[162:165], v217
	ds_read_b128 v[170:173], v213
	ds_read_b128 v[174:177], v213 offset:4096
	ds_read_b128 v[166:169], v217 offset:4096
	s_waitcnt lgkmcnt(6)
	v_mfma_f32_32x32x16_bf16 v[2:17], v[186:189], v[194:197], v[2:17]
	v_add_u32_e32 v210, s23, v210
	v_add_u32_e32 v214, s23, v214
	s_waitcnt lgkmcnt(5)
	v_mfma_f32_32x32x16_bf16 v[18:33], v[186:189], v[198:201], v[18:33]
	v_add_u32_e32 v211, s23, v211
	v_add_u32_e32 v215, s23, v215
	s_waitcnt lgkmcnt(4)
	v_mfma_f32_32x32x16_bf16 v[34:49], v[190:193], v[194:197], v[34:49]
	v_add_u32_e32 v212, s23, v212
	v_add_u32_e32 v216, s23, v216
	v_mfma_f32_32x32x16_bf16 v[50:65], v[190:193], v[198:201], v[50:65]
	v_add_u32_e32 v213, s23, v213
	v_add_u32_e32 v217, s23, v217
	s_waitcnt lgkmcnt(0)
	s_waitcnt vmcnt(6)
	s_barrier
	ds_read_b128 v[186:189], v214
	ds_read_b128 v[194:197], v210
	ds_read_b128 v[198:201], v210 offset:4096
	ds_read_b128 v[190:193], v214 offset:4096
	s_add_i32 s28, s20, s22
	s_add_i32 s29, s20, s25
	s_add_i32 m0, s28, 0x0
	v_mfma_f32_32x32x16_bf16 v[2:17], v[162:165], v[170:173], v[2:17]
	global_load_lds_dwordx4 v202, s[34:35]
	s_add_i32 m0, s28, 0x400
	v_mfma_f32_32x32x16_bf16 v[18:33], v[162:165], v[174:177], v[18:33]
	global_load_lds_dwordx4 v203, s[34:35]
	s_add_i32 m0, s28, 0x800
	v_mfma_f32_32x32x16_bf16 v[34:49], v[166:169], v[170:173], v[34:49]
	global_load_lds_dwordx4 v204, s[34:35]
	s_add_i32 m0, s28, 0xc00
	v_mfma_f32_32x32x16_bf16 v[50:65], v[166:169], v[174:177], v[50:65]
	global_load_lds_dwordx4 v205, s[34:35]
	ds_read_b128 v[162:165], v215
	ds_read_b128 v[170:173], v211
	ds_read_b128 v[174:177], v211 offset:4096
	ds_read_b128 v[166:169], v215 offset:4096
	s_waitcnt lgkmcnt(6)
	s_add_i32 m0, s29, 0x0
	v_mfma_f32_32x32x16_bf16 v[2:17], v[186:189], v[194:197], v[2:17]
	global_load_lds_dwordx4 v206, s[36:37]
	s_waitcnt lgkmcnt(5)
	s_add_i32 m0, s29, 0x400
	v_mfma_f32_32x32x16_bf16 v[18:33], v[186:189], v[198:201], v[18:33]
	global_load_lds_dwordx4 v207, s[36:37]
	s_waitcnt lgkmcnt(4)
	v_mfma_f32_32x32x16_bf16 v[34:49], v[190:193], v[194:197], v[34:49]
	s_add_u32 s34, s34, 0x80
	s_addc_u32 s35, s35, 0
	v_mfma_f32_32x32x16_bf16 v[50:65], v[190:193], v[198:201], v[50:65]
	s_add_u32 s36, s36, 0x80
	s_addc_u32 s37, s37, 0
	ds_read_b128 v[186:189], v216
	ds_read_b128 v[194:197], v212
	ds_read_b128 v[198:201], v212 offset:4096
	ds_read_b128 v[190:193], v216 offset:4096
	s_add_i32 s20, s20, 0xc000
	s_cmp_eq_u32 s20, 0x24000
	s_cselect_b32 s20, 0, s20
	s_waitcnt lgkmcnt(6)
	v_mfma_f32_32x32x16_bf16 v[2:17], v[162:165], v[170:173], v[2:17]
	s_add_i32 s30, s21, 0xc000
	s_waitcnt lgkmcnt(5)
	v_mfma_f32_32x32x16_bf16 v[18:33], v[162:165], v[174:177], v[18:33]
	s_cmp_eq_u32 s30, 0x24000
	s_waitcnt lgkmcnt(4)
	v_mfma_f32_32x32x16_bf16 v[34:49], v[166:169], v[170:173], v[34:49]
	s_cselect_b32 s30, 0, s30
	v_mfma_f32_32x32x16_bf16 v[50:65], v[166:169], v[174:177], v[50:65]
	s_sub_i32 s23, s30, s21
	s_mov_b32 s21, s30
	ds_read_b128 v[162:165], v217
	ds_read_b128 v[170:173], v213
	ds_read_b128 v[174:177], v213 offset:4096
	ds_read_b128 v[166:169], v217 offset:4096
	s_waitcnt lgkmcnt(6)
	v_mfma_f32_32x32x16_bf16 v[2:17], v[186:189], v[194:197], v[2:17]
	v_add_u32_e32 v210, s23, v210
	v_add_u32_e32 v214, s23, v214
	s_waitcnt lgkmcnt(5)
	v_mfma_f32_32x32x16_bf16 v[18:33], v[186:189], v[198:201], v[18:33]
	v_add_u32_e32 v211, s23, v211
	v_add_u32_e32 v215, s23, v215
	s_waitcnt lgkmcnt(4)
	v_mfma_f32_32x32x16_bf16 v[34:49], v[190:193], v[194:197], v[34:49]
	v_add_u32_e32 v212, s23, v212
	v_add_u32_e32 v216, s23, v216
	v_mfma_f32_32x32x16_bf16 v[50:65], v[190:193], v[198:201], v[50:65]
	v_add_u32_e32 v213, s23, v213
	v_add_u32_e32 v217, s23, v217
	s_waitcnt lgkmcnt(0)
	s_waitcnt vmcnt(6)
	s_barrier
	ds_read_b128 v[186:189], v214
	ds_read_b128 v[194:197], v210
	ds_read_b128 v[198:201], v210 offset:4096
	ds_read_b128 v[190:193], v214 offset:4096
	s_add_i32 s28, s20, s22
	s_add_i32 s29, s20, s25
	s_add_i32 m0, s28, 0x0
	v_mfma_f32_32x32x16_bf16 v[2:17], v[162:165], v[170:173], v[2:17]
	global_load_lds_dwordx4 v202, s[34:35]
	s_add_i32 m0, s28, 0x400
	v_mfma_f32_32x32x16_bf16 v[18:33], v[162:165], v[174:177], v[18:33]
	global_load_lds_dwordx4 v203, s[34:35]
	s_add_i32 m0, s28, 0x800
	v_mfma_f32_32x32x16_bf16 v[34:49], v[166:169], v[170:173], v[34:49]
	global_load_lds_dwordx4 v204, s[34:35]
	s_add_i32 m0, s28, 0xc00
	v_mfma_f32_32x32x16_bf16 v[50:65], v[166:169], v[174:177], v[50:65]
	global_load_lds_dwordx4 v205, s[34:35]
	ds_read_b128 v[162:165], v215
	ds_read_b128 v[170:173], v211
	ds_read_b128 v[174:177], v211 offset:4096
	ds_read_b128 v[166:169], v215 offset:4096
	s_waitcnt lgkmcnt(6)
	s_add_i32 m0, s29, 0x0
	v_mfma_f32_32x32x16_bf16 v[2:17], v[186:189], v[194:197], v[2:17]
	global_load_lds_dwordx4 v206, s[36:37]
	s_waitcnt lgkmcnt(5)
	s_add_i32 m0, s29, 0x400
	v_mfma_f32_32x32x16_bf16 v[18:33], v[186:189], v[198:201], v[18:33]
	global_load_lds_dwordx4 v207, s[36:37]
	s_waitcnt lgkmcnt(4)
	v_mfma_f32_32x32x16_bf16 v[34:49], v[190:193], v[194:197], v[34:49]
	s_add_u32 s34, s34, 0x80
	s_addc_u32 s35, s35, 0
	v_mfma_f32_32x32x16_bf16 v[50:65], v[190:193], v[198:201], v[50:65]
	s_add_u32 s36, s36, 0x80
	s_addc_u32 s37, s37, 0
	ds_read_b128 v[186:189], v216
	ds_read_b128 v[194:197], v212
	ds_read_b128 v[198:201], v212 offset:4096
	ds_read_b128 v[190:193], v216 offset:4096
	s_add_i32 s20, s20, 0xc000
	s_cmp_eq_u32 s20, 0x24000
	s_cselect_b32 s20, 0, s20
	s_waitcnt lgkmcnt(6)
	v_mfma_f32_32x32x16_bf16 v[2:17], v[162:165], v[170:173], v[2:17]
	s_add_i32 s30, s21, 0xc000
	s_waitcnt lgkmcnt(5)
	v_mfma_f32_32x32x16_bf16 v[18:33], v[162:165], v[174:177], v[18:33]
	s_cmp_eq_u32 s30, 0x24000
	s_waitcnt lgkmcnt(4)
	v_mfma_f32_32x32x16_bf16 v[34:49], v[166:169], v[170:173], v[34:49]
	s_cselect_b32 s30, 0, s30
	v_mfma_f32_32x32x16_bf16 v[50:65], v[166:169], v[174:177], v[50:65]
	s_sub_i32 s23, s30, s21
	s_mov_b32 s21, s30
	ds_read_b128 v[162:165], v217
	ds_read_b128 v[170:173], v213
	ds_read_b128 v[174:177], v213 offset:4096
	ds_read_b128 v[166:169], v217 offset:4096
	s_waitcnt lgkmcnt(6)
	v_mfma_f32_32x32x16_bf16 v[2:17], v[186:189], v[194:197], v[2:17]
	v_add_u32_e32 v210, s23, v210
	v_add_u32_e32 v214, s23, v214
	s_waitcnt lgkmcnt(5)
	v_mfma_f32_32x32x16_bf16 v[18:33], v[186:189], v[198:201], v[18:33]
	v_add_u32_e32 v211, s23, v211
	v_add_u32_e32 v215, s23, v215
	s_waitcnt lgkmcnt(4)
	v_mfma_f32_32x32x16_bf16 v[34:49], v[190:193], v[194:197], v[34:49]
	v_add_u32_e32 v212, s23, v212
	v_add_u32_e32 v216, s23, v216
	v_mfma_f32_32x32x16_bf16 v[50:65], v[190:193], v[198:201], v[50:65]
	v_add_u32_e32 v213, s23, v213
	v_add_u32_e32 v217, s23, v217
	s_waitcnt lgkmcnt(0)
	v_mfma_f32_32x32x16_bf16 v[2:17], v[162:165], v[170:173], v[2:17]
	v_mfma_f32_32x32x16_bf16 v[18:33], v[162:165], v[174:177], v[18:33]
	v_mfma_f32_32x32x16_bf16 v[34:49], v[166:169], v[170:173], v[34:49]
	v_mfma_f32_32x32x16_bf16 v[50:65], v[166:169], v[174:177], v[50:65]
	s_nop 15
	v_lshlrev_b32_e32 v220, 16, v130
	v_and_b32_e32 v221, 0xffff0000, v130
	v_pk_fma_f32 v[66:67], v[2:3], v[220:221], v[66:67]
	v_lshlrev_b32_e32 v222, 16, v131
	v_and_b32_e32 v223, 0xffff0000, v131
	v_pk_fma_f32 v[68:69], v[4:5], v[222:223], v[68:69]
	v_lshlrev_b32_e32 v224, 16, v132
	v_and_b32_e32 v225, 0xffff0000, v132
	v_pk_fma_f32 v[70:71], v[6:7], v[224:225], v[70:71]
	v_lshlrev_b32_e32 v226, 16, v133
	v_and_b32_e32 v227, 0xffff0000, v133
	v_pk_fma_f32 v[72:73], v[8:9], v[226:227], v[72:73]
	v_lshlrev_b32_e32 v220, 16, v134
	v_and_b32_e32 v221, 0xffff0000, v134
	v_pk_fma_f32 v[74:75], v[10:11], v[220:221], v[74:75]
	v_lshlrev_b32_e32 v222, 16, v135
	v_and_b32_e32 v223, 0xffff0000, v135
	v_pk_fma_f32 v[76:77], v[12:13], v[222:223], v[76:77]
	v_lshlrev_b32_e32 v224, 16, v136
	v_and_b32_e32 v225, 0xffff0000, v136
	v_pk_fma_f32 v[78:79], v[14:15], v[224:225], v[78:79]
	v_lshlrev_b32_e32 v226, 16, v137
	v_and_b32_e32 v227, 0xffff0000, v137
	v_pk_fma_f32 v[80:81], v[16:17], v[226:227], v[80:81]
	v_lshlrev_b32_e32 v220, 16, v138
	v_and_b32_e32 v221, 0xffff0000, v138
	v_pk_fma_f32 v[82:83], v[18:19], v[220:221], v[82:83]
	v_lshlrev_b32_e32 v222, 16, v139
	v_and_b32_e32 v223, 0xffff0000, v139
	v_pk_fma_f32 v[84:85], v[20:21], v[222:223], v[84:85]
	v_lshlrev_b32_e32 v224, 16, v140
	v_and_b32_e32 v225, 0xffff0000, v140
	v_pk_fma_f32 v[86:87], v[22:23], v[224:225], v[86:87]
	v_lshlrev_b32_e32 v226, 16, v141
	v_and_b32_e32 v227, 0xffff0000, v141
	v_pk_fma_f32 v[88:89], v[24:25], v[226:227], v[88:89]
	v_lshlrev_b32_e32 v220, 16, v142
	v_and_b32_e32 v221, 0xffff0000, v142
	v_pk_fma_f32 v[90:91], v[26:27], v[220:221], v[90:91]
	v_lshlrev_b32_e32 v222, 16, v143
	v_and_b32_e32 v223, 0xffff0000, v143
	v_pk_fma_f32 v[92:93], v[28:29], v[222:223], v[92:93]
	v_lshlrev_b32_e32 v224, 16, v144
	v_and_b32_e32 v225, 0xffff0000, v144
	v_pk_fma_f32 v[94:95], v[30:31], v[224:225], v[94:95]
	v_lshlrev_b32_e32 v226, 16, v145
	v_and_b32_e32 v227, 0xffff0000, v145
	v_pk_fma_f32 v[96:97], v[32:33], v[226:227], v[96:97]
	v_lshlrev_b32_e32 v220, 16, v146
	v_and_b32_e32 v221, 0xffff0000, v146
	v_pk_fma_f32 v[98:99], v[34:35], v[220:221], v[98:99]
	v_lshlrev_b32_e32 v222, 16, v147
	v_and_b32_e32 v223, 0xffff0000, v147
	v_pk_fma_f32 v[100:101], v[36:37], v[222:223], v[100:101]
	v_lshlrev_b32_e32 v224, 16, v148
	v_and_b32_e32 v225, 0xffff0000, v148
	v_pk_fma_f32 v[102:103], v[38:39], v[224:225], v[102:103]
	v_lshlrev_b32_e32 v226, 16, v149
	v_and_b32_e32 v227, 0xffff0000, v149
	v_pk_fma_f32 v[104:105], v[40:41], v[226:227], v[104:105]
	v_lshlrev_b32_e32 v220, 16, v150
	v_and_b32_e32 v221, 0xffff0000, v150
	v_pk_fma_f32 v[106:107], v[42:43], v[220:221], v[106:107]
	v_lshlrev_b32_e32 v222, 16, v151
	v_and_b32_e32 v223, 0xffff0000, v151
	v_pk_fma_f32 v[108:109], v[44:45], v[222:223], v[108:109]
	v_lshlrev_b32_e32 v224, 16, v152
	v_and_b32_e32 v225, 0xffff0000, v152
	v_pk_fma_f32 v[110:111], v[46:47], v[224:225], v[110:111]
	v_lshlrev_b32_e32 v226, 16, v153
	v_and_b32_e32 v227, 0xffff0000, v153
	v_pk_fma_f32 v[112:113], v[48:49], v[226:227], v[112:113]
	v_lshlrev_b32_e32 v220, 16, v154
	v_and_b32_e32 v221, 0xffff0000, v154
	v_pk_fma_f32 v[114:115], v[50:51], v[220:221], v[114:115]
	v_lshlrev_b32_e32 v222, 16, v155
	v_and_b32_e32 v223, 0xffff0000, v155
	v_pk_fma_f32 v[116:117], v[52:53], v[222:223], v[116:117]
	v_lshlrev_b32_e32 v224, 16, v156
	v_and_b32_e32 v225, 0xffff0000, v156
	v_pk_fma_f32 v[118:119], v[54:55], v[224:225], v[118:119]
	v_lshlrev_b32_e32 v226, 16, v157
	v_and_b32_e32 v227, 0xffff0000, v157
	v_pk_fma_f32 v[120:121], v[56:57], v[226:227], v[120:121]
	v_lshlrev_b32_e32 v220, 16, v158
	v_and_b32_e32 v221, 0xffff0000, v158
	v_pk_fma_f32 v[122:123], v[58:59], v[220:221], v[122:123]
	v_lshlrev_b32_e32 v222, 16, v159
	v_and_b32_e32 v223, 0xffff0000, v159
	v_pk_fma_f32 v[124:125], v[60:61], v[222:223], v[124:125]
	v_lshlrev_b32_e32 v224, 16, v160
	v_and_b32_e32 v225, 0xffff0000, v160
	v_pk_fma_f32 v[126:127], v[62:63], v[224:225], v[126:127]
	v_lshlrev_b32_e32 v226, 16, v161
	v_and_b32_e32 v227, 0xffff0000, v161
	v_pk_fma_f32 v[128:129], v[64:65], v[226:227], v[128:129]
	s_add_i32 s26, s26, 1
	s_cmp_lg_u32 s26, 4
	s_cbranch_scc1 .Lmg_iloop
	v_cvt_pk_bf16_f32 v220, v66, v67
	v_cvt_pk_bf16_f32 v221, v68, v69
	global_store_dwordx2 v178, v[220:221], s[42:43] offset:0
	v_cvt_pk_bf16_f32 v222, v70, v71
	v_cvt_pk_bf16_f32 v223, v72, v73
	global_store_dwordx2 v178, v[222:223], s[42:43] offset:16
	v_cvt_pk_bf16_f32 v224, v74, v75
	v_cvt_pk_bf16_f32 v225, v76, v77
	global_store_dwordx2 v178, v[224:225], s[42:43] offset:32
	v_cvt_pk_bf16_f32 v226, v78, v79
	v_cvt_pk_bf16_f32 v227, v80, v81
	global_store_dwordx2 v178, v[226:227], s[42:43] offset:48
	v_cvt_pk_bf16_f32 v220, v82, v83
	v_cvt_pk_bf16_f32 v221, v84, v85
	global_store_dwordx2 v179, v[220:221], s[42:43] offset:0
	v_cvt_pk_bf16_f32 v222, v86, v87
	v_cvt_pk_bf16_f32 v223, v88, v89
	global_store_dwordx2 v179, v[222:223], s[42:43] offset:16
	v_cvt_pk_bf16_f32 v224, v90, v91
	v_cvt_pk_bf16_f32 v225, v92, v93
	global_store_dwordx2 v179, v[224:225], s[42:43] offset:32
	v_cvt_pk_bf16_f32 v226, v94, v95
	v_cvt_pk_bf16_f32 v227, v96, v97
	global_store_dwordx2 v179, v[226:227], s[42:43] offset:48
	v_cvt_pk_bf16_f32 v220, v98, v99
	v_cvt_pk_bf16_f32 v221, v100, v101
	global_store_dwordx2 v178, v[220:221], s[42:43] offset:64
	v_cvt_pk_bf16_f32 v222, v102, v103
	v_cvt_pk_bf16_f32 v223, v104, v105
	global_store_dwordx2 v178, v[222:223], s[42:43] offset:80
	v_cvt_pk_bf16_f32 v224, v106, v107
	v_cvt_pk_bf16_f32 v225, v108, v109
	global_store_dwordx2 v178, v[224:225], s[42:43] offset:96
	v_cvt_pk_bf16_f32 v226, v110, v111
	v_cvt_pk_bf16_f32 v227, v112, v113
	global_store_dwordx2 v178, v[226:227], s[42:43] offset:112
	v_cvt_pk_bf16_f32 v220, v114, v115
	v_cvt_pk_bf16_f32 v221, v116, v117
	global_store_dwordx2 v179, v[220:221], s[42:43] offset:64
	v_cvt_pk_bf16_f32 v222, v118, v119
	v_cvt_pk_bf16_f32 v223, v120, v121
	global_store_dwordx2 v179, v[222:223], s[42:43] offset:80
	v_cvt_pk_bf16_f32 v224, v122, v123
	v_cvt_pk_bf16_f32 v225, v124, v125
	global_store_dwordx2 v179, v[224:225], s[42:43] offset:96
	v_cvt_pk_bf16_f32 v226, v126, v127
	v_cvt_pk_bf16_f32 v227, v128, v129
	global_store_dwordx2 v179, v[226:227], s[42:43] offset:112
	s_waitcnt vmcnt(0)
	s_barrier
	s_add_i32 s24, s24, s84
	s_cmpk_gt_i32 s24, 0x1ff
	s_cbranch_scc0 .Lmg_unit
